# XCD-local seams as a flat flag barrier: per-workgroup slot store + one L1-bypassing poll of the group's 32-slot line by wave 0, L1 invalidate on wave 1; no atomics/leader/release word
# baseline (speedup 1.0000x reference)
; __device__ __forceinline__ void xcd_barrier(const XcdBarrier& b) {
;     asm volatile("s_waitcnt vmcnt(0)" ::: "memory");
;     __syncthreads();
.LBB0_231:
	s_cmp_gt_i32 s31, 2
	s_cselect_b64 s[0:1], -1, 0
	s_and_b64 s[4:5], s[6:7], s[0:1]
	s_andn2_b64 vcc, exec, s[4:5]
	s_cbranch_vccnz .LBB0_285
	s_waitcnt vmcnt(0)
	s_waitcnt vmcnt(0) lgkmcnt(0)
	s_barrier
	v_readlane_b32 s101, v249, 48
	v_readlane_b32 s100, v249, 18
	s_nop 3
	s_cmp_eq_u32 s101, 0
	s_cbranch_scc1 .Lfb_orig_0
	s_cmp_eq_u32 s100, 1
	s_cbranch_scc1 .Lfb_inv_0
	s_cmp_lg_u32 s100, 0
	s_cbranch_scc1 .Lfb_done_0
	s_lshr_b32 s100, s92, 3
	s_and_b32 s99, s100, 7
	s_lshl_b32 s99, s99, 7
	s_add_i32 s99, s99, 0x183a00
	s_lshr_b32 s100, s100, 3
	s_lshl_b32 s100, s100, 2
	s_add_i32 s100, s100, s99
	v_mov_b32_e32 v0, s100
	v_mov_b32_e32 v1, 1
	global_store_dword v0, v1, s[28:29]
	v_and_b32_e32 v0, 31, v196
	v_lshl_add_u32 v0, v0, 2, s99
	s_mov_b32 s101, 0
.Lfb_poll_0:
	global_load_dword v2, v0, s[28:29] sc1
	s_waitcnt vmcnt(0)
	v_cmp_gt_u32_e32 vcc, 1, v2
	s_cbranch_vccz .Lfb_done_0
	s_sleep 1
	s_add_i32 s101, s101, 1
	s_cmp_lt_u32 s101, 0x2000
	s_cbranch_scc1 .Lfb_poll_0
	s_branch .Lfb_done_0

; __device__ __forceinline__ void xcd_barrier(const XcdBarrier& b) {
;     ...
;     __syncthreads();
;     if (threadIdx.x == 0) {
;         unsigned* bar = b.bar;
;         __builtin_amdgcn_s_waitcnt(0);
;         unsigned nloc = b.st[0], nx = b.st[1];
;         if (nloc == 0u) { xcd_barrier_complete(bar, b.x, nloc, nx); b.st[0] = nloc; b.st[1] = nx; }
.Lfb_done_0:
	s_waitcnt vmcnt(0)
	s_barrier
	s_branch .LBB0_285
.Lfb_orig_0:
	s_mov_b64 s[4:5], exec
	v_readlane_b32 s6, v249, 0
	v_readlane_b32 s7, v249, 1
	s_and_b64 s[6:7], s[4:5], s[6:7]
	s_mov_b64 exec, s[6:7]
	s_cbranch_execz .LBB0_284
	buffer_inv sc1
	s_add_i32 s3, 0, 0x23fc0
	v_mov_b32_e32 v0, s3
	s_waitcnt vmcnt(0) expcnt(0) lgkmcnt(0)
	ds_read_b32 v2, v0
	s_add_i32 s3, 0, 0x23fc4
	v_mov_b32_e32 v0, s3
	ds_read_b32 v0, v0
	s_waitcnt lgkmcnt(1)
	v_cmp_ne_u32_e32 vcc, 0, v2
	s_cbranch_vccnz .LBB0_248
	s_add_u32 s6, s28, 0x180200
	s_addc_u32 s7, s29, 0
	s_add_u32 s8, s28, 0x180400
	s_addc_u32 s9, s29, 0
	s_add_u32 s10, s28, 0x180500
	s_addc_u32 s11, s29, 0
	s_add_u32 s12, s28, 0x180600
	s_addc_u32 s13, s29, 0
	s_add_u32 s14, s28, 0x180700
	s_addc_u32 s15, s29, 0
	s_add_u32 s16, s28, 0x180800
	s_addc_u32 s17, s29, 0
	s_add_u32 s18, s28, 0x180900
	s_addc_u32 s19, s29, 0
	s_add_u32 s20, s28, 0x180a00
	s_addc_u32 s21, s29, 0
	s_add_u32 s34, s28, 0x180b00
	s_addc_u32 s35, s29, 0
	s_add_u32 s42, s28, 0x180c00
	s_addc_u32 s43, s29, 0
	s_add_u32 s46, s28, 0x180d00
	s_addc_u32 s47, s29, 0
	s_add_u32 s48, s28, 0x180e00
	s_addc_u32 s49, s29, 0
	s_add_u32 s50, s28, 0x180f00
	s_addc_u32 s51, s29, 0
	s_add_u32 s52, s28, 0x181000
	s_addc_u32 s53, s29, 0
	s_add_u32 s54, s28, 0x181100
	s_addc_u32 s55, s29, 0
	s_add_u32 s56, s28, 0x181200
	s_addc_u32 s57, s29, 0
	s_mul_i32 s3, s23, s96
	s_add_u32 s58, s28, 0x181300
	s_mul_i32 s3, s3, s22
	s_addc_u32 s59, s29, 0
	s_mov_b32 s66, 1
	v_mov_b32_e32 v16, 0
	s_branch .LBB0_236

; __device__ __forceinline__ void xcd_barrier(const XcdBarrier& b) {
;     asm volatile("s_waitcnt vmcnt(0)" ::: "memory");
;     __syncthreads();
.LBB0_425:
	s_cmp_gt_i32 s31, 4
	s_cselect_b64 s[0:1], -1, 0
	s_and_b64 s[4:5], s[6:7], s[0:1]
	s_andn2_b64 vcc, exec, s[4:5]
	s_cbranch_vccnz .LBB0_479
	s_waitcnt vmcnt(0)
	s_waitcnt vmcnt(0) lgkmcnt(0)
	s_barrier
	v_readlane_b32 s101, v249, 48
	v_readlane_b32 s100, v249, 18
	s_nop 3
	s_cmp_eq_u32 s101, 0
	s_cbranch_scc1 .Lfb_orig_1
	s_cmp_eq_u32 s100, 1
	s_cbranch_scc1 .Lfb_inv_1
	s_cmp_lg_u32 s100, 0
	s_cbranch_scc1 .Lfb_done_1
	s_lshr_b32 s100, s92, 3
	s_and_b32 s99, s100, 7
	s_lshl_b32 s99, s99, 7
	s_add_i32 s99, s99, 0x183a00
	s_lshr_b32 s100, s100, 3
	s_lshl_b32 s100, s100, 2
	s_add_i32 s100, s100, s99
	v_mov_b32_e32 v0, s100
	v_mov_b32_e32 v1, 2
	global_store_dword v0, v1, s[28:29]
	v_and_b32_e32 v0, 31, v196
	v_lshl_add_u32 v0, v0, 2, s99
	s_mov_b32 s101, 0
.Lfb_poll_1:
	global_load_dword v2, v0, s[28:29] sc1
	s_waitcnt vmcnt(0)
	v_cmp_gt_u32_e32 vcc, 2, v2
	s_cbranch_vccz .Lfb_done_1
	s_sleep 1
	s_add_i32 s101, s101, 1
	s_cmp_lt_u32 s101, 0x2000
	s_cbranch_scc1 .Lfb_poll_1
	s_branch .Lfb_done_1

; __device__ __forceinline__ void xcd_barrier(const XcdBarrier& b) {
;     ...
;     if (threadIdx.x == 0) {
;         unsigned* bar = b.bar;
;         __builtin_amdgcn_s_waitcnt(0);
;         unsigned nloc = b.st[0], nx = b.st[1];
;         if (nloc == 0u) { xcd_barrier_complete(bar, b.x, nloc, nx); b.st[0] = nloc; b.st[1] = nx; }
.Lfb_orig_1:
	s_mov_b64 s[4:5], exec
	v_readlane_b32 s6, v249, 0
	v_readlane_b32 s7, v249, 1
	s_and_b64 s[6:7], s[4:5], s[6:7]
	s_mov_b64 exec, s[6:7]
	s_cbranch_execz .LBB0_478
	buffer_inv sc1
	s_add_i32 s3, 0, 0x23fc0
	v_mov_b32_e32 v0, s3
	s_waitcnt vmcnt(0) expcnt(0) lgkmcnt(0)
	ds_read_b32 v2, v0
	s_add_i32 s3, 0, 0x23fc4
	v_mov_b32_e32 v0, s3
	ds_read_b32 v0, v0
	s_waitcnt lgkmcnt(1)
	v_cmp_ne_u32_e32 vcc, 0, v2
	s_cbranch_vccnz .LBB0_442
	s_add_u32 s6, s28, 0x180200
	s_addc_u32 s7, s29, 0
	s_add_u32 s8, s28, 0x180400
	s_addc_u32 s9, s29, 0
	s_add_u32 s10, s28, 0x180500
	s_addc_u32 s11, s29, 0
	s_add_u32 s12, s28, 0x180600
	s_addc_u32 s13, s29, 0
	s_add_u32 s14, s28, 0x180700
	s_addc_u32 s15, s29, 0
	s_add_u32 s16, s28, 0x180800
	s_addc_u32 s17, s29, 0
	s_add_u32 s18, s28, 0x180900
	s_addc_u32 s19, s29, 0
	s_add_u32 s20, s28, 0x180a00
	s_addc_u32 s21, s29, 0
	s_add_u32 s34, s28, 0x180b00
	s_addc_u32 s35, s29, 0
	s_add_u32 s42, s28, 0x180c00
	s_addc_u32 s43, s29, 0
	s_add_u32 s48, s28, 0x180d00
	s_addc_u32 s49, s29, 0
	s_add_u32 s50, s28, 0x180e00
	s_addc_u32 s51, s29, 0
	s_add_u32 s52, s28, 0x180f00
	s_addc_u32 s53, s29, 0
	s_add_u32 s54, s28, 0x181000
	s_addc_u32 s55, s29, 0
	s_add_u32 s56, s28, 0x181100
	s_addc_u32 s57, s29, 0
	s_add_u32 s58, s28, 0x181200
	s_addc_u32 s59, s29, 0
	s_mul_i32 s3, s23, s96
	s_add_u32 s60, s28, 0x181300
	s_mul_i32 s3, s3, s22
	s_addc_u32 s61, s29, 0
	s_mov_b32 s68, 1
	v_mov_b32_e32 v16, 0
	s_branch .LBB0_430

; __device__ __forceinline__ void xcd_barrier(const XcdBarrier& b) {
;     asm volatile("s_waitcnt vmcnt(0)" ::: "memory");
;     __syncthreads();
.LBB0_490:
	s_cmp_gt_i32 s31, 5
	s_cselect_b64 s[4:5], -1, 0
	s_and_b64 s[0:1], s[8:9], s[4:5]
	v_readlane_b32 s80, v249, 0
	s_andn2_b64 vcc, exec, s[0:1]
	v_readlane_b32 s81, v249, 1
	s_cbranch_vccnz .LBB0_544
	s_waitcnt vmcnt(0)
	s_waitcnt vmcnt(0) lgkmcnt(0)
	s_barrier
	v_readlane_b32 s101, v249, 48
	v_readlane_b32 s100, v249, 18
	s_nop 3
	s_cmp_eq_u32 s101, 0
	s_cbranch_scc1 .Lfb_orig_2
	s_cmp_eq_u32 s100, 1
	s_cbranch_scc1 .Lfb_inv_2
	s_cmp_lg_u32 s100, 0
	s_cbranch_scc1 .Lfb_done_2
	s_lshr_b32 s100, s92, 3
	s_and_b32 s99, s100, 7
	s_lshl_b32 s99, s99, 7
	s_add_i32 s99, s99, 0x183a00
	s_lshr_b32 s100, s100, 3
	s_lshl_b32 s100, s100, 2
	s_add_i32 s100, s100, s99
	v_mov_b32_e32 v0, s100
	v_mov_b32_e32 v1, 3
	global_store_dword v0, v1, s[28:29]
	v_and_b32_e32 v0, 31, v196
	v_lshl_add_u32 v0, v0, 2, s99
	s_mov_b32 s101, 0
.Lfb_poll_2:
	global_load_dword v2, v0, s[28:29] sc1
	s_waitcnt vmcnt(0)
	v_cmp_gt_u32_e32 vcc, 3, v2
	s_cbranch_vccz .Lfb_done_2
	s_sleep 1
	s_add_i32 s101, s101, 1
	s_cmp_lt_u32 s101, 0x2000
	s_cbranch_scc1 .Lfb_poll_2
	s_branch .Lfb_done_2

; __device__ __forceinline__ void xcd_barrier(const XcdBarrier& b) {
;     ...
;     if (threadIdx.x == 0) {
;         unsigned* bar = b.bar;
;         __builtin_amdgcn_s_waitcnt(0);
;         unsigned nloc = b.st[0], nx = b.st[1];
;         if (nloc == 0u) { xcd_barrier_complete(bar, b.x, nloc, nx); b.st[0] = nloc; b.st[1] = nx; }
.Lfb_orig_2:
	s_and_saveexec_b64 s[0:1], s[80:81]
	s_cbranch_execz .LBB0_543
	buffer_inv sc1
	s_add_i32 s3, 0, 0x23fc0
	v_mov_b32_e32 v0, s3
	s_waitcnt vmcnt(0) expcnt(0) lgkmcnt(0)
	ds_read_b32 v2, v0
	s_add_i32 s3, 0, 0x23fc4
	v_mov_b32_e32 v0, s3
	ds_read_b32 v0, v0
	s_waitcnt lgkmcnt(1)
	v_cmp_ne_u32_e32 vcc, 0, v2
	s_cbranch_vccnz .LBB0_507
	s_add_u32 s8, s28, 0x180200
	s_addc_u32 s9, s29, 0
	s_add_u32 s10, s28, 0x180400
	s_addc_u32 s11, s29, 0
	s_add_u32 s12, s28, 0x180500
	s_addc_u32 s13, s29, 0
	s_add_u32 s14, s28, 0x180600
	s_addc_u32 s15, s29, 0
	s_add_u32 s16, s28, 0x180700
	s_addc_u32 s17, s29, 0
	s_add_u32 s18, s28, 0x180800
	s_addc_u32 s19, s29, 0
	s_add_u32 s20, s28, 0x180900
	s_addc_u32 s21, s29, 0
	s_add_u32 s34, s28, 0x180a00
	s_addc_u32 s35, s29, 0
	s_add_u32 s48, s28, 0x180b00
	s_addc_u32 s49, s29, 0
	s_add_u32 s50, s28, 0x180c00
	s_addc_u32 s51, s29, 0
	s_add_u32 s52, s28, 0x180d00
	s_addc_u32 s53, s29, 0
	s_add_u32 s54, s28, 0x180e00
	s_addc_u32 s55, s29, 0
	s_add_u32 s56, s28, 0x180f00
	s_addc_u32 s57, s29, 0
	s_add_u32 s58, s28, 0x181000
	s_addc_u32 s59, s29, 0
	s_add_u32 s60, s28, 0x181100
	s_addc_u32 s61, s29, 0
	s_add_u32 s62, s28, 0x181200
	s_addc_u32 s63, s29, 0
	s_mul_i32 s3, s23, s96
	s_add_u32 s64, s28, 0x181300
	s_mul_i32 s3, s3, s22
	s_addc_u32 s65, s29, 0
	s_mov_b32 s72, 1
	v_mov_b32_e32 v16, 0
	s_branch .LBB0_495

; __device__ __forceinline__ void xcd_barrier(const XcdBarrier& b) {
;     asm volatile("s_waitcnt vmcnt(0)" ::: "memory");
;     __syncthreads();
.LBB0_552:
	s_cmp_gt_i32 s31, 6
	s_cselect_b64 s[4:5], -1, 0
	s_and_b64 s[6:7], s[48:49], s[4:5]
	s_andn2_b64 vcc, exec, s[6:7]
	s_cbranch_vccnz .LBB0_606
	s_waitcnt vmcnt(0)
	s_waitcnt vmcnt(0) lgkmcnt(0)
	s_barrier
	v_readlane_b32 s101, v249, 48
	v_readlane_b32 s100, v249, 18
	s_nop 3
	s_cmp_eq_u32 s101, 0
	s_cbranch_scc1 .Lfb_orig_3
	s_cmp_eq_u32 s100, 1
	s_cbranch_scc1 .Lfb_inv_3
	s_cmp_lg_u32 s100, 0
	s_cbranch_scc1 .Lfb_done_3
	s_lshr_b32 s100, s92, 3
	s_and_b32 s99, s100, 7
	s_lshl_b32 s99, s99, 7
	s_add_i32 s99, s99, 0x183a00
	s_lshr_b32 s100, s100, 3
	s_lshl_b32 s100, s100, 2
	s_add_i32 s100, s100, s99
	v_mov_b32_e32 v0, s100
	v_mov_b32_e32 v1, 4
	global_store_dword v0, v1, s[28:29]
	v_and_b32_e32 v0, 31, v196
	v_lshl_add_u32 v0, v0, 2, s99
	s_mov_b32 s101, 0
.Lfb_poll_3:
	global_load_dword v2, v0, s[28:29] sc1
	s_waitcnt vmcnt(0)
	v_cmp_gt_u32_e32 vcc, 4, v2
	s_cbranch_vccz .Lfb_done_3
	s_sleep 1
	s_add_i32 s101, s101, 1
	s_cmp_lt_u32 s101, 0x2000
	s_cbranch_scc1 .Lfb_poll_3
	s_branch .Lfb_done_3

; __device__ __forceinline__ void xcd_barrier(const XcdBarrier& b) {
;     ...
;     if (threadIdx.x == 0) {
;         unsigned* bar = b.bar;
;         __builtin_amdgcn_s_waitcnt(0);
;         unsigned nloc = b.st[0], nx = b.st[1];
;         if (nloc == 0u) { xcd_barrier_complete(bar, b.x, nloc, nx); b.st[0] = nloc; b.st[1] = nx; }
.Lfb_orig_3:
	s_and_saveexec_b64 s[6:7], s[80:81]
	s_cbranch_execz .LBB0_605
	buffer_inv sc1
	s_add_i32 s3, 0, 0x23fc0
	v_mov_b32_e32 v0, s3
	s_waitcnt vmcnt(0) expcnt(0) lgkmcnt(0)
	ds_read_b32 v2, v0
	s_add_i32 s3, 0, 0x23fc4
	v_mov_b32_e32 v0, s3
	ds_read_b32 v0, v0
	s_waitcnt lgkmcnt(1)
	v_cmp_ne_u32_e32 vcc, 0, v2
	s_cbranch_vccnz .LBB0_569
	s_add_u32 s8, s28, 0x180200
	s_addc_u32 s9, s29, 0
	s_add_u32 s10, s28, 0x180400
	s_addc_u32 s11, s29, 0
	s_add_u32 s12, s28, 0x180500
	s_addc_u32 s13, s29, 0
	s_add_u32 s14, s28, 0x180600
	s_addc_u32 s15, s29, 0
	s_add_u32 s16, s28, 0x180700
	s_addc_u32 s17, s29, 0
	s_add_u32 s18, s28, 0x180800
	s_addc_u32 s19, s29, 0
	s_add_u32 s20, s28, 0x180900
	s_addc_u32 s21, s29, 0
	s_add_u32 s34, s28, 0x180a00
	s_addc_u32 s35, s29, 0
	s_add_u32 s38, s28, 0x180b00
	s_addc_u32 s39, s29, 0
	s_add_u32 s46, s28, 0x180c00
	s_addc_u32 s47, s29, 0
	s_add_u32 s48, s28, 0x180d00
	s_addc_u32 s49, s29, 0
	s_add_u32 s50, s28, 0x180e00
	s_addc_u32 s51, s29, 0
	s_add_u32 s52, s28, 0x180f00
	s_addc_u32 s53, s29, 0
	s_add_u32 s54, s28, 0x181000
	s_addc_u32 s55, s29, 0
	s_add_u32 s56, s28, 0x181100
	s_addc_u32 s57, s29, 0
	s_add_u32 s58, s28, 0x181200
	s_addc_u32 s59, s29, 0
	s_mul_i32 s3, s23, s96
	s_add_u32 s60, s28, 0x181300
	s_mul_i32 s3, s3, s22
	s_addc_u32 s61, s29, 0
	s_mov_b32 s33, 1
	v_mov_b32_e32 v16, 0
	s_branch .LBB0_557

; __device__ __forceinline__ void xcd_barrier(const XcdBarrier& b) {
;     asm volatile("s_waitcnt vmcnt(0)" ::: "memory");
;     __syncthreads();
.LBB0_631:
	s_cmp_gt_i32 s31, 7
	s_cselect_b64 s[0:1], -1, 0
	s_and_b64 s[4:5], s[6:7], s[0:1]
	s_andn2_b64 vcc, exec, s[4:5]
	s_cbranch_vccnz .LBB0_685
	s_waitcnt vmcnt(0)
	s_waitcnt vmcnt(0) lgkmcnt(0)
	s_barrier
	v_readlane_b32 s101, v249, 48
	v_readlane_b32 s100, v249, 18
	s_nop 3
	s_cmp_eq_u32 s101, 0
	s_cbranch_scc1 .Lfb_orig_4
	s_cmp_eq_u32 s100, 1
	s_cbranch_scc1 .Lfb_inv_4
	s_cmp_lg_u32 s100, 0
	s_cbranch_scc1 .Lfb_done_4
	s_lshr_b32 s100, s92, 3
	s_and_b32 s99, s100, 7
	s_lshl_b32 s99, s99, 7
	s_add_i32 s99, s99, 0x183a00
	s_lshr_b32 s100, s100, 3
	s_lshl_b32 s100, s100, 2
	s_add_i32 s100, s100, s99
	v_mov_b32_e32 v0, s100
	v_mov_b32_e32 v1, 5
	global_store_dword v0, v1, s[28:29]
	v_and_b32_e32 v0, 31, v196
	v_lshl_add_u32 v0, v0, 2, s99
	s_mov_b32 s101, 0
.Lfb_poll_4:
	global_load_dword v2, v0, s[28:29] sc1
	s_waitcnt vmcnt(0)
	v_cmp_gt_u32_e32 vcc, 5, v2
	s_cbranch_vccz .Lfb_done_4
	s_sleep 1
	s_add_i32 s101, s101, 1
	s_cmp_lt_u32 s101, 0x2000
	s_cbranch_scc1 .Lfb_poll_4
	s_branch .Lfb_done_4

; __device__ __forceinline__ void xcd_barrier(const XcdBarrier& b) {
;     ...
;     if (threadIdx.x == 0) {
;         unsigned* bar = b.bar;
;         __builtin_amdgcn_s_waitcnt(0);
;         unsigned nloc = b.st[0], nx = b.st[1];
;         if (nloc == 0u) { xcd_barrier_complete(bar, b.x, nloc, nx); b.st[0] = nloc; b.st[1] = nx; }
.Lfb_orig_4:
	s_and_saveexec_b64 s[4:5], s[80:81]
	s_cbranch_execz .LBB0_684
	buffer_inv sc1
	s_add_i32 s3, 0, 0x23fc0
	v_mov_b32_e32 v0, s3
	s_waitcnt vmcnt(0) expcnt(0) lgkmcnt(0)
	ds_read_b32 v2, v0
	s_add_i32 s3, 0, 0x23fc4
	v_mov_b32_e32 v0, s3
	ds_read_b32 v0, v0
	s_waitcnt lgkmcnt(1)
	v_cmp_ne_u32_e32 vcc, 0, v2
	s_cbranch_vccnz .LBB0_648
	s_add_u32 s6, s28, 0x180200
	s_addc_u32 s7, s29, 0
	s_add_u32 s8, s28, 0x180400
	s_addc_u32 s9, s29, 0
	s_add_u32 s10, s28, 0x180500
	s_addc_u32 s11, s29, 0
	s_add_u32 s12, s28, 0x180600
	s_addc_u32 s13, s29, 0
	s_add_u32 s14, s28, 0x180700
	s_addc_u32 s15, s29, 0
	s_add_u32 s16, s28, 0x180800
	s_addc_u32 s17, s29, 0
	s_add_u32 s18, s28, 0x180900
	s_addc_u32 s19, s29, 0
	s_add_u32 s20, s28, 0x180a00
	s_addc_u32 s21, s29, 0
	s_add_u32 s34, s28, 0x180b00
	s_addc_u32 s35, s29, 0
	s_add_u32 s38, s28, 0x180c00
	s_addc_u32 s39, s29, 0
	s_add_u32 s44, s28, 0x180d00
	s_addc_u32 s45, s29, 0
	s_add_u32 s46, s28, 0x180e00
	s_addc_u32 s47, s29, 0
	s_add_u32 s48, s28, 0x180f00
	s_addc_u32 s49, s29, 0
	s_add_u32 s50, s28, 0x181000
	s_addc_u32 s51, s29, 0
	s_add_u32 s52, s28, 0x181100
	s_addc_u32 s53, s29, 0
	s_add_u32 s54, s28, 0x181200
	s_addc_u32 s55, s29, 0
	s_mul_i32 s3, s23, s96
	s_add_u32 s56, s28, 0x181300
	s_mul_i32 s3, s3, s22
	s_addc_u32 s57, s29, 0
	s_mov_b32 s33, 1
	v_mov_b32_e32 v16, 0
	s_branch .LBB0_636

; __device__ __forceinline__ void xcd_barrier(const XcdBarrier& b) {
;     asm volatile("s_waitcnt vmcnt(0)" ::: "memory");
;     __syncthreads();
.LBB0_817:
	s_cmp_gt_i32 s31, 9
	s_cselect_b64 s[0:1], -1, 0
	s_and_b64 s[4:5], s[6:7], s[0:1]
	s_andn2_b64 vcc, exec, s[4:5]
	s_cbranch_vccnz .LBB0_871
	s_waitcnt vmcnt(0)
	s_waitcnt vmcnt(0) lgkmcnt(0)
	s_barrier
	v_readlane_b32 s101, v249, 48
	v_readlane_b32 s100, v249, 18
	s_nop 3
	s_cmp_eq_u32 s101, 0
	s_cbranch_scc1 .Lfb_orig_5
	s_cmp_eq_u32 s100, 1
	s_cbranch_scc1 .Lfb_inv_5
	s_cmp_lg_u32 s100, 0
	s_cbranch_scc1 .Lfb_done_5
	s_lshr_b32 s100, s92, 3
	s_and_b32 s99, s100, 7
	s_lshl_b32 s99, s99, 7
	s_add_i32 s99, s99, 0x183a00
	s_lshr_b32 s100, s100, 3
	s_lshl_b32 s100, s100, 2
	s_add_i32 s100, s100, s99
	v_mov_b32_e32 v0, s100
	v_mov_b32_e32 v1, 6
	global_store_dword v0, v1, s[28:29]
	v_and_b32_e32 v0, 31, v196
	v_lshl_add_u32 v0, v0, 2, s99
	s_mov_b32 s101, 0
.Lfb_poll_5:
	global_load_dword v2, v0, s[28:29] sc1
	s_waitcnt vmcnt(0)
	v_cmp_gt_u32_e32 vcc, 6, v2
	s_cbranch_vccz .Lfb_done_5
	s_sleep 1
	s_add_i32 s101, s101, 1
	s_cmp_lt_u32 s101, 0x2000
	s_cbranch_scc1 .Lfb_poll_5
	s_branch .Lfb_done_5

; __device__ __forceinline__ void xcd_barrier(const XcdBarrier& b) {
;     asm volatile("s_waitcnt vmcnt(0)" ::: "memory");
;     __syncthreads();
.LBB0_918:
	s_cmp_gt_i32 s31, 10
	s_cselect_b64 s[0:1], -1, 0
	s_and_b64 s[4:5], s[8:9], s[0:1]
	s_andn2_b64 vcc, exec, s[4:5]
	s_cbranch_vccnz .LBB0_972
	s_waitcnt vmcnt(0)
	s_waitcnt vmcnt(0) lgkmcnt(0)
	s_barrier
	v_readlane_b32 s101, v249, 48
	v_readlane_b32 s100, v249, 18
	s_nop 3
	s_cmp_eq_u32 s101, 0
	s_cbranch_scc1 .Lfb_orig_6
	s_cmp_eq_u32 s100, 1
	s_cbranch_scc1 .Lfb_inv_6
	s_cmp_lg_u32 s100, 0
	s_cbranch_scc1 .Lfb_done_6
	s_lshr_b32 s100, s92, 3
	s_and_b32 s99, s100, 7
	s_lshl_b32 s99, s99, 7
	s_add_i32 s99, s99, 0x183a00
	s_lshr_b32 s100, s100, 3
	s_lshl_b32 s100, s100, 2
	s_add_i32 s100, s100, s99
	v_mov_b32_e32 v0, s100
	v_mov_b32_e32 v1, 7
	global_store_dword v0, v1, s[28:29]
	v_and_b32_e32 v0, 31, v196
	v_lshl_add_u32 v0, v0, 2, s99
	s_mov_b32 s101, 0
.Lfb_poll_6:
	global_load_dword v2, v0, s[28:29] sc1
	s_waitcnt vmcnt(0)
	v_cmp_gt_u32_e32 vcc, 7, v2
	s_cbranch_vccz .Lfb_done_6
	s_sleep 1
	s_add_i32 s101, s101, 1
	s_cmp_lt_u32 s101, 0x2000
	s_cbranch_scc1 .Lfb_poll_6
	s_branch .Lfb_done_6

; __device__ __forceinline__ void xcd_barrier(const XcdBarrier& b) {
;     asm volatile("s_waitcnt vmcnt(0)" ::: "memory");
;     __syncthreads();
.LBB0_1007:
	s_cmp_gt_i32 s31, 11
	s_cselect_b64 s[0:1], -1, 0
	s_and_b64 s[4:5], s[6:7], s[0:1]
	s_andn2_b64 vcc, exec, s[4:5]
	s_cbranch_vccnz .LBB0_1061
	s_waitcnt vmcnt(0)
	s_waitcnt vmcnt(0) lgkmcnt(0)
	s_barrier
	v_readlane_b32 s101, v249, 48
	v_readlane_b32 s100, v249, 18
	s_nop 3
	s_cmp_eq_u32 s101, 0
	s_cbranch_scc1 .Lfb_orig_7
	s_cmp_eq_u32 s100, 1
	s_cbranch_scc1 .Lfb_inv_7
	s_cmp_lg_u32 s100, 0
	s_cbranch_scc1 .Lfb_done_7
	s_lshr_b32 s100, s92, 3
	s_and_b32 s99, s100, 7
	s_lshl_b32 s99, s99, 7
	s_add_i32 s99, s99, 0x183a00
	s_lshr_b32 s100, s100, 3
	s_lshl_b32 s100, s100, 2
	s_add_i32 s100, s100, s99
	v_mov_b32_e32 v0, s100
	v_mov_b32_e32 v1, 8
	global_store_dword v0, v1, s[28:29]
	v_and_b32_e32 v0, 31, v196
	v_lshl_add_u32 v0, v0, 2, s99
	s_mov_b32 s101, 0
.Lfb_poll_7:
	global_load_dword v2, v0, s[28:29] sc1
	s_waitcnt vmcnt(0)
	v_cmp_gt_u32_e32 vcc, 8, v2
	s_cbranch_vccz .Lfb_done_7
	s_sleep 1
	s_add_i32 s101, s101, 1
	s_cmp_lt_u32 s101, 0x2000
	s_cbranch_scc1 .Lfb_poll_7
	s_branch .Lfb_done_7

; __device__ __forceinline__ void xcd_barrier(const XcdBarrier& b) {
;     asm volatile("s_waitcnt vmcnt(0)" ::: "memory");
;     __syncthreads();
.LBB0_1453:
	s_cmp_gt_u32 s31, 13
	s_cselect_b64 s[0:1], -1, 0
	s_and_b64 s[0:1], s[10:11], s[0:1]
	s_andn2_b64 vcc, exec, s[0:1]
	s_cbranch_vccnz .LBB0_1507
	s_waitcnt vmcnt(0)
	s_waitcnt vmcnt(0) lgkmcnt(0)
	s_barrier
	v_readlane_b32 s101, v249, 48
	v_readlane_b32 s100, v249, 18
	s_nop 3
	s_cmp_eq_u32 s101, 0
	s_cbranch_scc1 .Lfb_orig_8
	s_cmp_eq_u32 s100, 1
	s_cbranch_scc1 .Lfb_inv_8
	s_cmp_lg_u32 s100, 0
	s_cbranch_scc1 .Lfb_done_8
	s_lshr_b32 s100, s92, 3
	s_and_b32 s99, s100, 7
	s_lshl_b32 s99, s99, 7
	s_add_i32 s99, s99, 0x183a00
	s_lshr_b32 s100, s100, 3
	s_lshl_b32 s100, s100, 2
	s_add_i32 s100, s100, s99
	v_mov_b32_e32 v0, s100
	v_mov_b32_e32 v1, 9
	global_store_dword v0, v1, s[28:29]
	v_and_b32_e32 v0, 31, v196
	v_lshl_add_u32 v0, v0, 2, s99
	s_mov_b32 s101, 0
.Lfb_poll_8:
	global_load_dword v2, v0, s[28:29] sc1
	s_waitcnt vmcnt(0)
	v_cmp_gt_u32_e32 vcc, 9, v2
	s_cbranch_vccz .Lfb_done_8
	s_sleep 1
	s_add_i32 s101, s101, 1
	s_cmp_lt_u32 s101, 0x2000
	s_cbranch_scc1 .Lfb_poll_8
	s_branch .Lfb_done_8

; __device__ __forceinline__ void xcd_barrier(const XcdBarrier& b) {
;     ...
;     if (threadIdx.x == 0) {
;         unsigned* bar = b.bar;
;         __builtin_amdgcn_s_waitcnt(0);
;         unsigned nloc = b.st[0], nx = b.st[1];
;         if (nloc == 0u) { xcd_barrier_complete(bar, b.x, nloc, nx); b.st[0] = nloc; b.st[1] = nx; }
.Lfb_orig_8:
	s_and_saveexec_b64 s[0:1], s[80:81]
	s_cbranch_execz .LBB0_1506
	buffer_inv sc1
	s_add_i32 s3, 0, 0x23fc0
	v_mov_b32_e32 v0, s3
	s_waitcnt vmcnt(0) expcnt(0) lgkmcnt(0)
	ds_read_b32 v2, v0
	s_add_i32 s3, 0, 0x23fc4
	v_mov_b32_e32 v0, s3
	ds_read_b32 v0, v0
	s_waitcnt lgkmcnt(1)
	v_cmp_ne_u32_e32 vcc, 0, v2
	s_cbranch_vccnz .LBB0_1470
	s_add_u32 s4, s28, 0x180200
	s_addc_u32 s5, s29, 0
	s_add_u32 s6, s28, 0x180400
	s_addc_u32 s7, s29, 0
	s_add_u32 s8, s28, 0x180500
	s_addc_u32 s9, s29, 0
	s_add_u32 s10, s28, 0x180600
	s_addc_u32 s11, s29, 0
	s_add_u32 s12, s28, 0x180700
	s_addc_u32 s13, s29, 0
	s_add_u32 s14, s28, 0x180800
	s_addc_u32 s15, s29, 0
	s_add_u32 s16, s28, 0x180900
	s_addc_u32 s17, s29, 0
	s_add_u32 s18, s28, 0x180a00
	s_addc_u32 s19, s29, 0
	s_add_u32 s20, s28, 0x180b00
	s_addc_u32 s21, s29, 0
	s_add_u32 s34, s28, 0x180c00
	s_addc_u32 s35, s29, 0
	s_add_u32 s38, s28, 0x180d00
	s_addc_u32 s39, s29, 0
	s_add_u32 s44, s28, 0x180e00
	s_addc_u32 s45, s29, 0
	s_add_u32 s46, s28, 0x180f00
	s_addc_u32 s47, s29, 0
	s_add_u32 s48, s28, 0x181000
	s_addc_u32 s49, s29, 0
	s_add_u32 s50, s28, 0x181100
	s_addc_u32 s51, s29, 0
	s_add_u32 s52, s28, 0x181200
	s_addc_u32 s53, s29, 0
	s_mul_i32 s3, s23, s96
	s_add_u32 s54, s28, 0x181300
	s_mul_i32 s3, s3, s22
	s_addc_u32 s55, s29, 0
	s_mov_b32 s33, 1
	v_mov_b32_e32 v16, 0
	s_branch .LBB0_1458

; __device__ __forceinline__ void xcd_barrier(const XcdBarrier& b) {
;     asm volatile("s_waitcnt vmcnt(0)" ::: "memory");
;     __syncthreads();
.LBB0_1561:
	s_cmp_gt_i32 s31, 15
	s_cselect_b64 s[0:1], -1, 0
	s_and_b64 s[4:5], s[38:39], s[0:1]
	s_andn2_b64 vcc, exec, s[4:5]
	s_cbranch_vccnz .LBB0_1615
	s_waitcnt vmcnt(0)
	s_waitcnt vmcnt(0) lgkmcnt(0)
	s_barrier
	v_readlane_b32 s101, v249, 48
	v_readlane_b32 s100, v249, 18
	s_nop 3
	s_cmp_eq_u32 s101, 0
	s_cbranch_scc1 .Lfb_orig_9
	s_cmp_eq_u32 s100, 1
	s_cbranch_scc1 .Lfb_inv_9
	s_cmp_lg_u32 s100, 0
	s_cbranch_scc1 .Lfb_done_9
	s_lshr_b32 s100, s92, 3
	s_and_b32 s99, s100, 7
	s_lshl_b32 s99, s99, 7
	s_add_i32 s99, s99, 0x183a00
	s_lshr_b32 s100, s100, 3
	s_lshl_b32 s100, s100, 2
	s_add_i32 s100, s100, s99
	v_mov_b32_e32 v0, s100
	v_mov_b32_e32 v1, 10
	global_store_dword v0, v1, s[28:29]
	v_and_b32_e32 v0, 31, v196
	v_lshl_add_u32 v0, v0, 2, s99
	s_mov_b32 s101, 0
.Lfb_poll_9:
	global_load_dword v2, v0, s[28:29] sc1
	s_waitcnt vmcnt(0)
	v_cmp_gt_u32_e32 vcc, 10, v2
	s_cbranch_vccz .Lfb_done_9
	s_sleep 1
	s_add_i32 s101, s101, 1
	s_cmp_lt_u32 s101, 0x2000
	s_cbranch_scc1 .Lfb_poll_9
	s_branch .Lfb_done_9

; __device__ __forceinline__ void xcd_barrier(const XcdBarrier& b) {
;     ...
;     if (threadIdx.x == 0) {
;         unsigned* bar = b.bar;
;         __builtin_amdgcn_s_waitcnt(0);
;         unsigned nloc = b.st[0], nx = b.st[1];
;         if (nloc == 0u) { xcd_barrier_complete(bar, b.x, nloc, nx); b.st[0] = nloc; b.st[1] = nx; }
.Lfb_orig_9:
	s_and_saveexec_b64 s[4:5], s[80:81]
	s_cbranch_execz .LBB0_1614
	buffer_inv sc1
	s_add_i32 s3, 0, 0x23fc0
	v_mov_b32_e32 v0, s3
	s_waitcnt vmcnt(0) expcnt(0) lgkmcnt(0)
	ds_read_b32 v2, v0
	s_add_i32 s3, 0, 0x23fc4
	v_mov_b32_e32 v0, s3
	ds_read_b32 v0, v0
	s_waitcnt lgkmcnt(1)
	v_cmp_ne_u32_e32 vcc, 0, v2
	s_cbranch_vccnz .LBB0_1578
	s_add_u32 s6, s28, 0x180200
	s_addc_u32 s7, s29, 0
	s_add_u32 s8, s28, 0x180400
	s_addc_u32 s9, s29, 0
	s_add_u32 s10, s28, 0x180500
	s_addc_u32 s11, s29, 0
	s_add_u32 s12, s28, 0x180600
	s_addc_u32 s13, s29, 0
	s_add_u32 s14, s28, 0x180700
	s_addc_u32 s15, s29, 0
	s_add_u32 s16, s28, 0x180800
	s_addc_u32 s17, s29, 0
	s_add_u32 s20, s28, 0x180900
	s_addc_u32 s21, s29, 0
	s_add_u32 s34, s28, 0x180a00
	s_addc_u32 s35, s29, 0
	s_add_u32 s38, s28, 0x180b00
	s_addc_u32 s39, s29, 0
	s_add_u32 s42, s28, 0x180c00
	s_addc_u32 s43, s29, 0
	s_add_u32 s44, s28, 0x180d00
	s_addc_u32 s45, s29, 0
	s_add_u32 s46, s28, 0x180e00
	s_addc_u32 s47, s29, 0
	s_add_u32 s48, s28, 0x180f00
	s_addc_u32 s49, s29, 0
	s_add_u32 s50, s28, 0x181000
	s_addc_u32 s51, s29, 0
	s_add_u32 s52, s28, 0x181100
	s_addc_u32 s53, s29, 0
	s_add_u32 s54, s28, 0x181200
	s_addc_u32 s55, s29, 0
	s_mul_i32 s3, s23, s96
	s_add_u32 s56, s28, 0x181300
	s_mul_i32 s3, s3, s22
	s_addc_u32 s57, s29, 0
	s_mov_b32 s33, 1
	v_mov_b32_e32 v16, 0
	s_branch .LBB0_1566

; __device__ __forceinline__ void xcd_barrier(const XcdBarrier& b) {
;     asm volatile("s_waitcnt vmcnt(0)" ::: "memory");
;     __syncthreads();
.LBB0_1747:
	s_cmp_gt_i32 s31, 17
	s_cselect_b64 s[0:1], -1, 0
	s_and_b64 s[4:5], s[6:7], s[0:1]
	s_andn2_b64 vcc, exec, s[4:5]
	s_cbranch_vccnz .LBB0_1801
	s_waitcnt vmcnt(0)
	s_waitcnt vmcnt(0) lgkmcnt(0)
	s_barrier
	v_readlane_b32 s101, v249, 48
	v_readlane_b32 s100, v249, 18
	s_nop 3
	s_cmp_eq_u32 s101, 0
	s_cbranch_scc1 .Lfb_orig_10
	s_cmp_eq_u32 s100, 1
	s_cbranch_scc1 .Lfb_inv_10
	s_cmp_lg_u32 s100, 0
	s_cbranch_scc1 .Lfb_done_10
	s_lshr_b32 s100, s92, 3
	s_and_b32 s99, s100, 7
	s_lshl_b32 s99, s99, 7
	s_add_i32 s99, s99, 0x183a00
	s_lshr_b32 s100, s100, 3
	s_lshl_b32 s100, s100, 2
	s_add_i32 s100, s100, s99
	v_mov_b32_e32 v0, s100
	v_mov_b32_e32 v1, 11
	global_store_dword v0, v1, s[28:29]
	v_and_b32_e32 v0, 31, v196
	v_lshl_add_u32 v0, v0, 2, s99
	s_mov_b32 s101, 0
.Lfb_poll_10:
	global_load_dword v2, v0, s[28:29] sc1
	s_waitcnt vmcnt(0)
	v_cmp_gt_u32_e32 vcc, 11, v2
	s_cbranch_vccz .Lfb_done_10
	s_sleep 1
	s_add_i32 s101, s101, 1
	s_cmp_lt_u32 s101, 0x2000
	s_cbranch_scc1 .Lfb_poll_10
	s_branch .Lfb_done_10

; __device__ __forceinline__ void xcd_barrier(const XcdBarrier& b) {
;     ...
;     if (threadIdx.x == 0) {
;         unsigned* bar = b.bar;
;         __builtin_amdgcn_s_waitcnt(0);
;         unsigned nloc = b.st[0], nx = b.st[1];
;         if (nloc == 0u) { xcd_barrier_complete(bar, b.x, nloc, nx); b.st[0] = nloc; b.st[1] = nx; }
.Lfb_orig_10:
	s_and_saveexec_b64 s[4:5], s[80:81]
	s_cbranch_execz .LBB0_1800
	buffer_inv sc1
	s_add_i32 s3, 0, 0x23fc0
	v_mov_b32_e32 v0, s3
	s_waitcnt vmcnt(0) expcnt(0) lgkmcnt(0)
	ds_read_b32 v2, v0
	s_add_i32 s3, 0, 0x23fc4
	v_mov_b32_e32 v0, s3
	ds_read_b32 v0, v0
	s_waitcnt lgkmcnt(1)
	v_cmp_ne_u32_e32 vcc, 0, v2
	s_cbranch_vccnz .LBB0_1764
	s_add_u32 s6, s28, 0x180200
	s_addc_u32 s7, s29, 0
	s_add_u32 s8, s28, 0x180400
	s_addc_u32 s9, s29, 0
	s_add_u32 s10, s28, 0x180500
	s_addc_u32 s11, s29, 0
	s_add_u32 s12, s28, 0x180600
	s_addc_u32 s13, s29, 0
	s_add_u32 s14, s28, 0x180700
	s_addc_u32 s15, s29, 0
	s_add_u32 s16, s28, 0x180800
	s_addc_u32 s17, s29, 0
	s_add_u32 s18, s28, 0x180900
	s_addc_u32 s19, s29, 0
	s_add_u32 s20, s28, 0x180a00
	s_addc_u32 s21, s29, 0
	s_add_u32 s34, s28, 0x180b00
	s_addc_u32 s35, s29, 0
	s_add_u32 s38, s28, 0x180c00
	s_addc_u32 s39, s29, 0
	s_add_u32 s42, s28, 0x180d00
	s_addc_u32 s43, s29, 0
	s_add_u32 s44, s28, 0x180e00
	s_addc_u32 s45, s29, 0
	s_add_u32 s46, s28, 0x180f00
	s_addc_u32 s47, s29, 0
	s_add_u32 s48, s28, 0x181000
	s_addc_u32 s49, s29, 0
	s_add_u32 s50, s28, 0x181100
	s_addc_u32 s51, s29, 0
	s_add_u32 s52, s28, 0x181200
	s_addc_u32 s53, s29, 0
	s_mul_i32 s3, s23, s96
	s_add_u32 s54, s28, 0x181300
	s_mul_i32 s3, s3, s22
	s_addc_u32 s55, s29, 0
	s_mov_b32 s33, 1
	v_mov_b32_e32 v16, 0
	s_branch .LBB0_1752

; __device__ __forceinline__ void xcd_barrier(const XcdBarrier& b) {
;     asm volatile("s_waitcnt vmcnt(0)" ::: "memory");
;     __syncthreads();
.LBB0_1848:
	s_cmp_gt_i32 s31, 18
	s_cselect_b64 s[0:1], -1, 0
	s_and_b64 s[2:3], s[8:9], s[0:1]
	s_andn2_b64 vcc, exec, s[2:3]
	s_cbranch_vccnz .LBB0_1902
	s_waitcnt vmcnt(0)
	s_waitcnt vmcnt(0) lgkmcnt(0)
	s_barrier
	v_readlane_b32 s101, v249, 48
	v_readlane_b32 s100, v249, 18
	s_nop 3
	s_cmp_eq_u32 s101, 0
	s_cbranch_scc1 .Lfb_orig_11
	s_cmp_eq_u32 s100, 1
	s_cbranch_scc1 .Lfb_inv_11
	s_cmp_lg_u32 s100, 0
	s_cbranch_scc1 .Lfb_done_11
	s_lshr_b32 s100, s92, 3
	s_and_b32 s99, s100, 7
	s_lshl_b32 s99, s99, 7
	s_add_i32 s99, s99, 0x183a00
	s_lshr_b32 s100, s100, 3
	s_lshl_b32 s100, s100, 2
	s_add_i32 s100, s100, s99
	v_mov_b32_e32 v0, s100
	v_mov_b32_e32 v1, 12
	global_store_dword v0, v1, s[28:29]
	v_and_b32_e32 v0, 31, v196
	v_lshl_add_u32 v0, v0, 2, s99
	s_mov_b32 s101, 0
.Lfb_poll_11:
	global_load_dword v2, v0, s[28:29] sc1
	s_waitcnt vmcnt(0)
	v_cmp_gt_u32_e32 vcc, 12, v2
	s_cbranch_vccz .Lfb_done_11
	s_sleep 1
	s_add_i32 s101, s101, 1
	s_cmp_lt_u32 s101, 0x2000
	s_cbranch_scc1 .Lfb_poll_11
	s_branch .Lfb_done_11

; __device__ __forceinline__ void xcd_barrier(const XcdBarrier& b) {
;     ...
;     if (threadIdx.x == 0) {
;         unsigned* bar = b.bar;
;         __builtin_amdgcn_s_waitcnt(0);
;         unsigned nloc = b.st[0], nx = b.st[1];
;         if (nloc == 0u) { xcd_barrier_complete(bar, b.x, nloc, nx); b.st[0] = nloc; b.st[1] = nx; }
.Lfb_orig_11:
	s_and_saveexec_b64 s[2:3], s[80:81]
	s_cbranch_execz .LBB0_1901
	buffer_inv sc1
	s_add_i32 s4, 0, 0x23fc0
	v_mov_b32_e32 v0, s4
	s_waitcnt vmcnt(0) expcnt(0) lgkmcnt(0)
	ds_read_b32 v2, v0
	s_add_i32 s4, 0, 0x23fc4
	v_mov_b32_e32 v0, s4
	ds_read_b32 v0, v0
	s_waitcnt lgkmcnt(1)
	v_cmp_ne_u32_e32 vcc, 0, v2
	s_cbranch_vccnz .LBB0_1865
	s_add_u32 s4, s28, 0x180200
	s_addc_u32 s5, s29, 0
	s_add_u32 s6, s28, 0x180400
	s_addc_u32 s7, s29, 0
	s_add_u32 s8, s28, 0x180500
	s_addc_u32 s9, s29, 0
	s_add_u32 s10, s28, 0x180600
	s_addc_u32 s11, s29, 0
	s_add_u32 s12, s28, 0x180700
	s_addc_u32 s13, s29, 0
	s_add_u32 s14, s28, 0x180800
	s_addc_u32 s15, s29, 0
	s_add_u32 s16, s28, 0x180900
	s_addc_u32 s17, s29, 0
	s_add_u32 s18, s28, 0x180a00
	s_addc_u32 s19, s29, 0
	s_add_u32 s20, s28, 0x180b00
	s_addc_u32 s21, s29, 0
	s_add_u32 s34, s28, 0x180c00
	s_addc_u32 s35, s29, 0
	s_add_u32 s36, s28, 0x180d00
	s_addc_u32 s37, s29, 0
	s_add_u32 s38, s28, 0x180e00
	s_addc_u32 s39, s29, 0
	s_add_u32 s40, s28, 0x180f00
	s_addc_u32 s41, s29, 0
	s_add_u32 s42, s28, 0x181000
	s_addc_u32 s43, s29, 0
	s_add_u32 s44, s28, 0x181100
	s_addc_u32 s45, s29, 0
	s_add_u32 s46, s28, 0x181200
	s_addc_u32 s47, s29, 0
	s_mul_i32 s23, s23, s96
	s_add_u32 s48, s28, 0x181300
	s_mul_i32 s23, s23, s22
	s_addc_u32 s49, s29, 0
	s_mov_b32 s31, 1
	v_mov_b32_e32 v16, 0
	s_branch .LBB0_1853
